# speedup vs baseline: 1.0568x; 1.0038x over previous
; #define LAS __attribute__((address_space(3)))
; __device__ __forceinline__ void p2_prep(const Ctx& C0) {
;     ...
;         for (int it = C.bid; it < 512; it += C.G) {
;             const int b = it >> 7, s0 = (it & 127) * 64;
; #pragma unroll
;             for (int i = 0; i < 8; ++i) {
;                 const int chunk = tid + 512 * i, row = chunk >> 6, cc = (chunk & 63) * 8;
;                 const u32x4 v = *(const u32x4*)(PROJ + (size_t)(b * 8192 + s0 + row) * 2048 + 1536 + cc);
;                 LAS unsigned* d = (LAS unsigned*)(vt + row * 514 + cc);
.LBB0_384:
	s_sub_i32 s7, s9, s7
	s_add_i32 s7, s7, -1
	s_cmpk_gt_i32 s7, 0x1ff
	s_cbranch_scc1 .LBB0_387
	v_add_u32_e32 v3, 0x200, v182
	v_lshrrev_b32_e32 v6, 6, v3
	v_add_u32_e32 v3, 0x600, v182
	v_lshlrev_b32_e32 v0, 14, v182
	s_waitcnt vmcnt(2)
	v_lshrrev_b32_e32 v8, 6, v3
	v_add_u32_e32 v3, 0xa00, v182
	v_and_b32_e32 v2, 0x3f0, v156
	v_lshrrev_b32_e32 v4, 6, v182
	v_and_b32_e32 v12, 0xfc000, v0
	v_mov_b32_e32 v13, 0
	v_lshrrev_b32_e32 v10, 6, v3
	v_add_u32_e32 v3, 0xe00, v182
	v_add_u32_e32 v23, 0, v2
	v_lshl_add_u64 v[0:1], s[78:79], 0, v[12:13]
	v_mul_u32_u24_e32 v14, 0x404, v4
	v_lshrrev_b32_e32 v12, 6, v3
	s_mov_b64 s[4:5], 0x10000000
	v_mul_u32_u24_e32 v15, 0x404, v6
	v_mul_u32_u24_e32 v17, 0x404, v8
	v_mul_u32_u24_e32 v20, 0x404, v10
	v_mul_u32_u24_e32 v24, 0x404, v12
	v_mov_b32_e32 v3, v13
	v_add_u32_e32 v13, v23, v14
	s_mov_b32 s1, 0
	v_lshl_add_u64 v[0:1], v[0:1], 0, s[4:5]
	v_lshl_add_u32 v5, v182, 1, 0
	v_or_b32_e32 v7, 16, v4
	v_or_b32_e32 v9, 32, v4
	v_or_b32_e32 v11, 48, v4
	v_lshl_add_u64 v[2:3], s[44:45], 0, v[2:3]
	s_lshl_b32 s4, s7, 6
	s_lshl_b32 s5, s9, 6
	v_add_u32_e32 v14, v23, v15
	v_add_u32_e32 v15, 0x4040, v13
	v_add_u32_e32 v16, 0x4048, v13
	v_add_u32_e32 v17, v23, v17
	v_add_u32_e32 v18, 0x8080, v13
	v_add_u32_e32 v19, 0x8088, v13
	v_add_u32_e32 v20, v23, v20
	v_add_u32_e32 v21, 0xc0c0, v13
	v_add_u32_e32 v22, 0xc0c8, v13
	v_add_u32_e32 v23, v23, v24
